# dsa_topk emit pass: one pair of LDS counter atomics per loop trip (4 elements) with per-element lane prefixes, on top of permlane-swap score loop
# speedup vs baseline: 1.0066x; 1.0066x over previous
; #define LAS __attribute__((address_space(3)))
; __device__ __forceinline__ unsigned f2key(float f) { const unsigned u = __float_as_uint(f); return (u & 0x80000000u) ? ~u : (u | 0x80000000u); }
; __device__ __forceinline__ void dsa_topk(const bf16_t* DP, const bf16_t* KIN, int* SEL, LAS unsigned char* lds, int widk) {
;     ...
;             for (int sb = 0; sb < nq; sb += 512) { const int s4 = sb + 4 * sub; const bool in4 = s4 < nq;
;                 f32x4 v4 = {0.f, 0.f, 0.f, 0.f}; if (in4) v4 = *(const LAS f32x4*)(row + s4);
; #pragma unroll
;                 for (int e = 0; e < 4; ++e) { const int s = s4 + e; const bool in = s < nq; const float v = v4[e]; const int bin = DSA_BIN(v);
;                     const bool gsel = in && bin > bA;
;                     const unsigned long long gm = __ballot(gsel);
;                     if (gm) { const int leader = __builtin_ctzll(gm); unsigned base = 0u;
;                         if (lane == leader) base = __hip_atomic_fetch_add(misc + q * 4 + 2, (unsigned)__builtin_popcountll(gm), __ATOMIC_RELAXED, __HIP_MEMORY_SCOPE_WORKGROUP);
;                         base = (unsigned)__builtin_amdgcn_readlane((int)base, leader);
;                         const unsigned pos = base + (unsigned)__builtin_popcountll(gm & ((1ull << lane) - 1ull));
;                         if (gsel && pos < 256u) selrow[pos] = s; }
;                     if (in && bin == bA) { const unsigned cp = __hip_atomic_fetch_add(misc + q * 4 + 3, 1u, __ATOMIC_RELAXED, __HIP_MEMORY_SCOPE_WORKGROUP); if (cp < 256u) { lst[2 * cp] = f2key(v); lst[2 * cp + 1] = (unsigned)s; } } }
;             }
.LBB0_516:
	v_add_u32_e32 v163, s64, v134
	v_cmp_ge_i32_e32 vcc, s92, v163
	v_mov_b32_e32 v164, 0
	v_mov_b32_e32 v165, 0
	v_mov_b32_e32 v166, 0
	v_mov_b32_e32 v167, 0
	s_and_saveexec_b64 s[62:63], vcc
	ds_read_b128 v[164:167], v12
	s_or_b64 exec, exec, s[62:63]
	v_add_u32_e32 v188, 1, v163
	v_add_u32_e32 v189, 2, v163
	v_add_u32_e32 v190, 3, v163
	v_mov_b32_e32 v183, 0
	s_mov_b32 s0, 0
	s_mov_b32 s1, 0
	s_waitcnt lgkmcnt(0)
	v_sub_f32_e32 v180, v164, v10
	v_mul_f32_e32 v180, v11, v180
	v_cvt_i32_f32_e32 v180, v180
	v_med3_i32 v168, v180, 0, v247
	v_cmp_ge_i32_e64 s[34:35], s92, v163
	v_cmp_lt_i32_e32 vcc, s95, v168
	s_and_b64 vcc, s[34:35], vcc
	v_mbcnt_lo_u32_b32 v180, vcc_lo, 0
	v_mbcnt_hi_u32_b32 v180, vcc_hi, v180
	v_add_u32_e32 v172, s0, v180
	s_bcnt1_i32_b64 s36, vcc
	s_add_i32 s0, s0, s36
	v_cmp_eq_u32_e32 vcc, s95, v168
	s_and_b64 vcc, s[34:35], vcc
	v_mbcnt_lo_u32_b32 v180, vcc_lo, 0
	v_mbcnt_hi_u32_b32 v180, vcc_hi, v180
	v_add_u32_e32 v176, s1, v180
	s_bcnt1_i32_b64 s36, vcc
	s_add_i32 s1, s1, s36
	v_sub_f32_e32 v180, v165, v10
	v_mul_f32_e32 v180, v11, v180
	v_cvt_i32_f32_e32 v180, v180
	v_med3_i32 v169, v180, 0, v247
	v_cmp_gt_i32_e64 s[34:35], s92, v163
	v_cmp_lt_i32_e32 vcc, s95, v169
	s_and_b64 vcc, s[34:35], vcc
	v_mbcnt_lo_u32_b32 v180, vcc_lo, 0
	v_mbcnt_hi_u32_b32 v180, vcc_hi, v180
	v_add_u32_e32 v173, s0, v180
	s_bcnt1_i32_b64 s36, vcc
	s_add_i32 s0, s0, s36
	v_cmp_eq_u32_e32 vcc, s95, v169
	s_and_b64 vcc, s[34:35], vcc
	v_mbcnt_lo_u32_b32 v180, vcc_lo, 0
	v_mbcnt_hi_u32_b32 v180, vcc_hi, v180
	v_add_u32_e32 v177, s1, v180
	s_bcnt1_i32_b64 s36, vcc
	s_add_i32 s1, s1, s36
	v_sub_f32_e32 v180, v166, v10
	v_mul_f32_e32 v180, v11, v180
	v_cvt_i32_f32_e32 v180, v180
	v_med3_i32 v170, v180, 0, v247
	v_cmp_ge_i32_e64 s[34:35], s92, v189
	v_cmp_lt_i32_e32 vcc, s95, v170
	s_and_b64 vcc, s[34:35], vcc
	v_mbcnt_lo_u32_b32 v180, vcc_lo, 0
	v_mbcnt_hi_u32_b32 v180, vcc_hi, v180
	v_add_u32_e32 v174, s0, v180
	s_bcnt1_i32_b64 s36, vcc
	s_add_i32 s0, s0, s36
	v_cmp_eq_u32_e32 vcc, s95, v170
	s_and_b64 vcc, s[34:35], vcc
	v_mbcnt_lo_u32_b32 v180, vcc_lo, 0
	v_mbcnt_hi_u32_b32 v180, vcc_hi, v180
	v_add_u32_e32 v178, s1, v180
	s_bcnt1_i32_b64 s36, vcc
	s_add_i32 s1, s1, s36
	v_sub_f32_e32 v180, v167, v10
	v_mul_f32_e32 v180, v11, v180
	v_cvt_i32_f32_e32 v180, v180
	v_med3_i32 v171, v180, 0, v247
	v_cmp_ge_i32_e64 s[34:35], s92, v190
	v_cmp_lt_i32_e32 vcc, s95, v171
	s_and_b64 vcc, s[34:35], vcc
	v_mbcnt_lo_u32_b32 v180, vcc_lo, 0
	v_mbcnt_hi_u32_b32 v180, vcc_hi, v180
	v_add_u32_e32 v175, s0, v180
	s_bcnt1_i32_b64 s36, vcc
	s_add_i32 s0, s0, s36
	v_cmp_eq_u32_e32 vcc, s95, v171
	s_and_b64 vcc, s[34:35], vcc
	v_mbcnt_lo_u32_b32 v180, vcc_lo, 0
	v_mbcnt_hi_u32_b32 v180, vcc_hi, v180
	v_add_u32_e32 v179, s1, v180
	s_bcnt1_i32_b64 s36, vcc
	s_add_i32 s1, s1, s36
	s_or_b32 s36, s0, s1
	s_cmp_eq_u32 s36, 0
	s_cbranch_scc1 .Lemit_next
	v_cmp_eq_u32_e32 vcc, 0, v101
	s_and_saveexec_b64 s[62:63], vcc
	s_add_i32 s36, s89, 0x21008
	v_mov_b32_e32 v180, s36
	v_mov_b32_e32 v181, s0
	ds_add_rtn_u32 v186, v180, v181
	s_add_i32 s36, s89, 0x2100c
	v_mov_b32_e32 v184, s36
	v_mov_b32_e32 v185, s1
	ds_add_rtn_u32 v187, v184, v185
	s_or_b64 exec, exec, s[62:63]
	s_waitcnt lgkmcnt(0)
	v_readfirstlane_b32 s36, v186
	v_readfirstlane_b32 s37, v187
	v_cmp_ge_i32_e64 s[34:35], s92, v163
	v_cmp_lt_i32_e32 vcc, s95, v168
	s_and_b64 s[30:31], s[34:35], vcc
	v_add_u32_e32 v182, s36, v172
	v_cmp_gt_u32_e32 vcc, 0x100, v182
	s_and_b64 s[30:31], s[30:31], vcc
	s_and_saveexec_b64 s[62:63], s[30:31]
	v_lshl_add_u64 v[184:185], v[182:183], 2, s[56:57]
	global_store_dword v[184:185], v163, off
	s_or_b64 exec, exec, s[62:63]
	v_cmp_eq_u32_e32 vcc, s95, v168
	s_and_b64 s[30:31], s[34:35], vcc
	v_add_u32_e32 v180, s37, v176
	v_cmp_gt_u32_e32 vcc, 0x100, v180
	s_and_b64 s[30:31], s[30:31], vcc
	s_and_saveexec_b64 s[62:63], s[30:31]
	v_not_b32_e32 v184, v164
	v_or_b32_e32 v186, 0x80000000, v164
	v_cmp_gt_i32_e32 vcc, 0, v164
	v_lshl_add_u32 v180, v180, 3, s79
	s_nop 0
	v_cndmask_b32_e32 v184, v186, v184, vcc
	v_mov_b32_e32 v185, v163
	ds_write_b64 v180, v[184:185]
	s_or_b64 exec, exec, s[62:63]
	v_cmp_gt_i32_e64 s[34:35], s92, v163
	v_cmp_lt_i32_e32 vcc, s95, v169
	s_and_b64 s[30:31], s[34:35], vcc
	v_add_u32_e32 v182, s36, v173
	v_cmp_gt_u32_e32 vcc, 0x100, v182
	s_and_b64 s[30:31], s[30:31], vcc
	s_and_saveexec_b64 s[62:63], s[30:31]
	v_lshl_add_u64 v[184:185], v[182:183], 2, s[56:57]
	global_store_dword v[184:185], v188, off
	s_or_b64 exec, exec, s[62:63]
	v_cmp_eq_u32_e32 vcc, s95, v169
	s_and_b64 s[30:31], s[34:35], vcc
	v_add_u32_e32 v180, s37, v177
	v_cmp_gt_u32_e32 vcc, 0x100, v180
	s_and_b64 s[30:31], s[30:31], vcc
	s_and_saveexec_b64 s[62:63], s[30:31]
	v_not_b32_e32 v184, v165
	v_or_b32_e32 v186, 0x80000000, v165
	v_cmp_gt_i32_e32 vcc, 0, v165
	v_lshl_add_u32 v180, v180, 3, s79
	s_nop 0
	v_cndmask_b32_e32 v184, v186, v184, vcc
	v_mov_b32_e32 v185, v188
	ds_write_b64 v180, v[184:185]
	s_or_b64 exec, exec, s[62:63]
	v_cmp_ge_i32_e64 s[34:35], s92, v189
	v_cmp_lt_i32_e32 vcc, s95, v170
	s_and_b64 s[30:31], s[34:35], vcc
	v_add_u32_e32 v182, s36, v174
	v_cmp_gt_u32_e32 vcc, 0x100, v182
	s_and_b64 s[30:31], s[30:31], vcc
	s_and_saveexec_b64 s[62:63], s[30:31]
	v_lshl_add_u64 v[184:185], v[182:183], 2, s[56:57]
	global_store_dword v[184:185], v189, off
	s_or_b64 exec, exec, s[62:63]
	v_cmp_eq_u32_e32 vcc, s95, v170
	s_and_b64 s[30:31], s[34:35], vcc
	v_add_u32_e32 v180, s37, v178
	v_cmp_gt_u32_e32 vcc, 0x100, v180
	s_and_b64 s[30:31], s[30:31], vcc
	s_and_saveexec_b64 s[62:63], s[30:31]
	v_not_b32_e32 v184, v166
	v_or_b32_e32 v186, 0x80000000, v166
	v_cmp_gt_i32_e32 vcc, 0, v166
	v_lshl_add_u32 v180, v180, 3, s79
	s_nop 0
	v_cndmask_b32_e32 v184, v186, v184, vcc
	v_mov_b32_e32 v185, v189
	ds_write_b64 v180, v[184:185]
	s_or_b64 exec, exec, s[62:63]
	v_cmp_ge_i32_e64 s[34:35], s92, v190
	v_cmp_lt_i32_e32 vcc, s95, v171
	s_and_b64 s[30:31], s[34:35], vcc
	v_add_u32_e32 v182, s36, v175
	v_cmp_gt_u32_e32 vcc, 0x100, v182
	s_and_b64 s[30:31], s[30:31], vcc
	s_and_saveexec_b64 s[62:63], s[30:31]
	v_lshl_add_u64 v[184:185], v[182:183], 2, s[56:57]
	global_store_dword v[184:185], v190, off
	s_or_b64 exec, exec, s[62:63]
	v_cmp_eq_u32_e32 vcc, s95, v171
	s_and_b64 s[30:31], s[34:35], vcc
	v_add_u32_e32 v180, s37, v179
	v_cmp_gt_u32_e32 vcc, 0x100, v180
	s_and_b64 s[30:31], s[30:31], vcc
	s_and_saveexec_b64 s[62:63], s[30:31]
	v_not_b32_e32 v184, v167
	v_or_b32_e32 v186, 0x80000000, v167
	v_cmp_gt_i32_e32 vcc, 0, v167
	v_lshl_add_u32 v180, v180, 3, s79
	s_nop 0
	v_cndmask_b32_e32 v184, v186, v184, vcc
	v_mov_b32_e32 v185, v190
	ds_write_b64 v180, v[184:185]
	s_or_b64 exec, exec, s[62:63]
.Lemit_next:
	s_branch .LBB0_515
